# grid-barrier poll loops sleep 6 instead of 1 between polls of the generation word (less polling traffic while the last workgroups finish)
# baseline (speedup 1.0000x reference)
.LBB0_43:
	s_and_b32 s17, s8, 0xff
	s_mov_b64 s[28:29], -1
	s_cmp_lg_u32 s17, 0
	s_mov_b64 s[34:35], -1
	s_sleep 6
	s_cbranch_scc0 .LBB0_46
	s_and_b64 vcc, exec, s[34:35]
	s_cbranch_vccz .LBB0_42
